# c3 accO MFMA LDS reads software-pipelined (4-deep); c1 kdT exp block de-serialized (batched LDS reads)
# speedup vs baseline: 1.0246x; 1.0006x over previous
; __device__ __forceinline__ bf16_t f2bf(float f) { return (bf16_t)(pk2(f, 0.f) & 0xffffu); }
; __device__ __forceinline__ void unpack8(const u32x4 w, float* o) { o[0] = bflo(w.x); o[1] = bfhi(w.x); o[2] = bflo(w.y); o[3] = bfhi(w.y); o[4] = bflo(w.z); o[5] = bfhi(w.z); o[6] = bflo(w.w); o[7] = bfhi(w.w); }
; __device__ __forceinline__ void gla_c1(const Args& a, int l, unsigned char* sm, const bf16_t* __restrict__ PC, const bf16_t* __restrict__ PLR, bf16_t* __restrict__ UPD, float* __restrict__ DEC) {
;     ...
;         {
;             const int j = tid >> 3, d0 = (tid & 7) * 16;
;             float kv[16]; unpack8(kraw[0], kv); unpack8(kraw[1], kv + 8);
; #pragma unroll
;             for (int e = 0; e < 16; ++e) { const int d = d0 + e; kdT[d * 72 + j] = f2bf(kv[e] * __expf(Gb[jb * 129 + d] - Gb[j * 129 + d])); }
;         }
.LBB0_245:
	s_or_b64 exec, exec, s[6:7]
	s_and_b64 s[0:1], s[0:1], exec
	s_cselect_b32 s2, 0x7efc, 0
	v_add_u32_e32 v16, s2, v68
	s_waitcnt lgkmcnt(0)
	s_barrier
	ds_read2_b32 v[202:203], v16 offset1:1
	ds_read2_b32 v[204:205], v16 offset0:2 offset1:3
	ds_read2_b32 v[206:207], v16 offset0:4 offset1:5
	ds_read2_b32 v[208:209], v16 offset0:6 offset1:7
	ds_read2_b32 v[210:211], v16 offset0:8 offset1:9
	ds_read2_b32 v[212:213], v16 offset0:10 offset1:11
	ds_read2_b32 v[214:215], v16 offset0:12 offset1:13
	ds_read2_b32 v[216:217], v16 offset0:14 offset1:15
	ds_read2_b32 v[218:219], v70 offset1:1
	ds_read2_b32 v[220:221], v70 offset0:2 offset1:3
	ds_read2_b32 v[222:223], v70 offset0:4 offset1:5
	ds_read2_b32 v[224:225], v70 offset0:6 offset1:7
	ds_read2_b32 v[226:227], v70 offset0:8 offset1:9
	ds_read2_b32 v[228:229], v70 offset0:10 offset1:11
	ds_read2_b32 v[230:231], v70 offset0:12 offset1:13
	ds_read2_b32 v[232:233], v70 offset0:14 offset1:15
	v_lshlrev_b32_e32 v234, 16, v4
	v_and_b32_e32 v235, 0xffff0000, v4
	v_lshlrev_b32_e32 v236, 16, v5
	v_and_b32_e32 v237, 0xffff0000, v5
	v_lshlrev_b32_e32 v238, 16, v6
	v_and_b32_e32 v239, 0xffff0000, v6
	v_lshlrev_b32_e32 v240, 16, v7
	v_and_b32_e32 v241, 0xffff0000, v7
	v_lshlrev_b32_e32 v242, 16, v0
	v_and_b32_e32 v243, 0xffff0000, v0
	v_lshlrev_b32_e32 v172, 16, v1
	v_and_b32_e32 v173, 0xffff0000, v1
	v_lshlrev_b32_e32 v174, 16, v2
	v_and_b32_e32 v175, 0xffff0000, v2
	v_lshlrev_b32_e32 v176, 16, v3
	v_and_b32_e32 v177, 0xffff0000, v3
	s_ashr_i32 s29, s28, 31
	s_lshl_b64 s[0:1], s[28:29], 16
	v_readlane_b32 s4, v246, 31
	v_readlane_b32 s5, v246, 32
	s_nop 1
	s_add_u32 s0, s4, s0
	s_addc_u32 s1, s5, s1
	s_waitcnt lgkmcnt(0)
	v_sub_f32_e32 v202, v202, v218
	v_sub_f32_e32 v203, v203, v219
	v_sub_f32_e32 v204, v204, v220
	v_sub_f32_e32 v205, v205, v221
	v_sub_f32_e32 v206, v206, v222
	v_sub_f32_e32 v207, v207, v223
	v_sub_f32_e32 v208, v208, v224
	v_sub_f32_e32 v209, v209, v225
	v_sub_f32_e32 v210, v210, v226
	v_sub_f32_e32 v211, v211, v227
	v_sub_f32_e32 v212, v212, v228
	v_sub_f32_e32 v213, v213, v229
	v_sub_f32_e32 v214, v214, v230
	v_sub_f32_e32 v215, v215, v231
	v_sub_f32_e32 v216, v216, v232
	v_sub_f32_e32 v217, v217, v233
	v_mul_f32_e32 v202, 0x3fb8aa3b, v202
	v_mul_f32_e32 v203, 0x3fb8aa3b, v203
	v_mul_f32_e32 v204, 0x3fb8aa3b, v204
	v_mul_f32_e32 v205, 0x3fb8aa3b, v205
	v_mul_f32_e32 v206, 0x3fb8aa3b, v206
	v_mul_f32_e32 v207, 0x3fb8aa3b, v207
	v_mul_f32_e32 v208, 0x3fb8aa3b, v208
	v_mul_f32_e32 v209, 0x3fb8aa3b, v209
	v_mul_f32_e32 v210, 0x3fb8aa3b, v210
	v_mul_f32_e32 v211, 0x3fb8aa3b, v211
	v_mul_f32_e32 v212, 0x3fb8aa3b, v212
	v_mul_f32_e32 v213, 0x3fb8aa3b, v213
	v_mul_f32_e32 v214, 0x3fb8aa3b, v214
	v_mul_f32_e32 v215, 0x3fb8aa3b, v215
	v_mul_f32_e32 v216, 0x3fb8aa3b, v216
	v_mul_f32_e32 v217, 0x3fb8aa3b, v217
	v_exp_f32_e32 v202, v202
	v_exp_f32_e32 v203, v203
	v_exp_f32_e32 v204, v204
	v_exp_f32_e32 v205, v205
	v_exp_f32_e32 v206, v206
	v_exp_f32_e32 v207, v207
	v_exp_f32_e32 v208, v208
	v_exp_f32_e32 v209, v209
	v_exp_f32_e32 v210, v210
	v_exp_f32_e32 v211, v211
	v_exp_f32_e32 v212, v212
	v_exp_f32_e32 v213, v213
	v_exp_f32_e32 v214, v214
	v_exp_f32_e32 v215, v215
	v_exp_f32_e32 v216, v216
	v_exp_f32_e32 v217, v217
	v_mul_f32_e32 v202, v202, v234
	v_mul_f32_e32 v203, v203, v235
	v_mul_f32_e32 v204, v204, v236
	v_mul_f32_e32 v205, v205, v237
	v_mul_f32_e32 v206, v206, v238
	v_mul_f32_e32 v207, v207, v239
	v_mul_f32_e32 v208, v208, v240
	v_mul_f32_e32 v209, v209, v241
	v_mul_f32_e32 v210, v210, v242
	v_mul_f32_e32 v211, v211, v243
	v_mul_f32_e32 v212, v212, v172
	v_mul_f32_e32 v213, v213, v173
	v_mul_f32_e32 v214, v214, v174
	v_mul_f32_e32 v215, v215, v175
	v_mul_f32_e32 v216, v216, v176
	v_mul_f32_e32 v217, v217, v177
	v_cvt_pk_bf16_f32 v202, v202, v65
	v_cvt_pk_bf16_f32 v203, v203, v65
	v_cvt_pk_bf16_f32 v204, v204, v65
	v_cvt_pk_bf16_f32 v205, v205, v65
	v_cvt_pk_bf16_f32 v206, v206, v65
	v_cvt_pk_bf16_f32 v207, v207, v65
	v_cvt_pk_bf16_f32 v208, v208, v65
	v_cvt_pk_bf16_f32 v209, v209, v65
	v_cvt_pk_bf16_f32 v210, v210, v65
	v_cvt_pk_bf16_f32 v211, v211, v65
	v_cvt_pk_bf16_f32 v212, v212, v65
	v_cvt_pk_bf16_f32 v213, v213, v65
	v_cvt_pk_bf16_f32 v214, v214, v65
	v_cvt_pk_bf16_f32 v215, v215, v65
	v_cvt_pk_bf16_f32 v216, v216, v65
	v_cvt_pk_bf16_f32 v217, v217, v65
	ds_write_b16 v71, v202 offset:47872
	ds_write_b16 v71, v203 offset:48016
	ds_write_b16 v71, v204 offset:48160
	ds_write_b16 v71, v205 offset:48304
	ds_write_b16 v71, v206 offset:48448
	ds_write_b16 v71, v207 offset:48592
	ds_write_b16 v71, v208 offset:48736
	ds_write_b16 v71, v209 offset:48880
	ds_write_b16 v71, v210 offset:49024
	ds_write_b16 v71, v211 offset:49168
	ds_write_b16 v71, v212 offset:49312
	ds_write_b16 v71, v213 offset:49456
	ds_write_b16 v71, v214 offset:49600
	ds_write_b16 v71, v215 offset:49744
	ds_write_b16 v71, v216 offset:49888
	ds_write_b16 v71, v217 offset:50032
	s_waitcnt lgkmcnt(0)
	s_barrier
; __device__ __forceinline__ void gla_c1(const Args& a, int l, unsigned char* sm, const bf16_t* __restrict__ PC, const bf16_t* __restrict__ PLR, bf16_t* __restrict__ UPD, float* __restrict__ DEC) {
;     ...
;         f32x16 acc[4];
; #pragma unroll
;         for (int nt = 0; nt < 4; ++nt)
; #pragma unroll
;             for (int e = 0; e < 16; ++e) acc[nt][e] = 0.f;
; #pragma unroll
;         for (int ks = 0; ks < 4; ++ks) {
;             const bf16x8 av = *(const bf16x8*)(vT + (32 * wid + r) * 72 + ks * 16 + 8 * h);
; #pragma unroll
;             for (int nt = 0; nt < 4; ++nt) { const bf16x8 bv = *(const bf16x8*)(kdT + (32 * nt + r) * 72 + ks * 16 + 8 * h); acc[nt] = __builtin_amdgcn_mfma_f32_32x32x16_bf16(av, bv, acc[nt], 0, 0, 0); }
;         }
	ds_read_b128 v[0:3], v123
	ds_read_b128 v[126:129], v123 offset:32
	ds_read_b128 v[4:7], v124 offset:47872
	ds_read_b128 v[130:133], v124 offset:47904
	s_waitcnt lgkmcnt(1)
	v_mfma_f32_32x32x16_bf16 v[48:63], v[0:3], v[4:7], 0
	ds_read_b128 v[4:7], v124 offset:52480
	s_waitcnt lgkmcnt(1)
	v_mfma_f32_32x32x16_bf16 v[48:63], v[126:129], v[130:133], v[48:63]
	ds_read_b128 v[130:133], v124 offset:52512
	s_waitcnt lgkmcnt(1)
	v_mfma_f32_32x32x16_bf16 v[32:47], v[0:3], v[4:7], 0
	ds_read_b128 v[4:7], v124 offset:57088
	s_waitcnt lgkmcnt(1)
	v_mfma_f32_32x32x16_bf16 v[32:47], v[126:129], v[130:133], v[32:47]
	ds_read_b128 v[130:133], v124 offset:57120
	s_waitcnt lgkmcnt(1)
	v_mfma_f32_32x32x16_bf16 v[16:31], v[0:3], v[4:7], 0
	ds_read_b128 v[4:7], v124 offset:61696
	s_waitcnt lgkmcnt(1)
	v_mfma_f32_32x32x16_bf16 v[16:31], v[126:129], v[130:133], v[16:31]
	ds_read_b128 v[130:133], v124 offset:61728
	s_waitcnt lgkmcnt(1)
	v_mfma_f32_32x32x16_bf16 v[0:15], v[0:3], v[4:7], 0
	s_waitcnt lgkmcnt(0)
	v_mfma_f32_32x32x16_bf16 v[0:15], v[126:129], v[130:133], v[0:15]
	ds_read_b128 v[126:129], v123 offset:64
	ds_read_b128 v[130:133], v124 offset:47936
	s_waitcnt lgkmcnt(0)
	v_mfma_f32_32x32x16_bf16 v[48:63], v[126:129], v[130:133], v[48:63]
	ds_read_b128 v[130:133], v124 offset:52544
	s_waitcnt lgkmcnt(0)
	v_mfma_f32_32x32x16_bf16 v[32:47], v[126:129], v[130:133], v[32:47]
	ds_read_b128 v[130:133], v124 offset:57152
	s_waitcnt lgkmcnt(0)
	v_mfma_f32_32x32x16_bf16 v[16:31], v[126:129], v[130:133], v[16:31]
	ds_read_b128 v[130:133], v124 offset:61760
	s_waitcnt lgkmcnt(0)
	v_mfma_f32_32x32x16_bf16 v[0:15], v[126:129], v[130:133], v[0:15]
	ds_read_b128 v[126:129], v123 offset:96
	ds_read_b128 v[130:133], v124 offset:47968
	s_waitcnt lgkmcnt(0)
	v_mfma_f32_32x32x16_bf16 v[48:63], v[126:129], v[130:133], v[48:63]
	ds_read_b128 v[130:133], v124 offset:52576
	s_waitcnt lgkmcnt(0)
	v_mfma_f32_32x32x16_bf16 v[32:47], v[126:129], v[130:133], v[32:47]
	ds_read_b128 v[130:133], v124 offset:57184
	s_waitcnt lgkmcnt(0)
	v_mfma_f32_32x32x16_bf16 v[16:31], v[126:129], v[130:133], v[16:31]
	ds_read_b128 v[130:133], v124 offset:61792
	v_cvt_pk_bf16_f32 v48, v48, v65
	s_waitcnt lgkmcnt(0)
; __device__ __forceinline__ bf16_t f2bf(float f) { return (bf16_t)(pk2(f, 0.f) & 0xffffu); }
; __device__ __forceinline__ void gla_c1(const Args& a, int l, unsigned char* sm, const bf16_t* __restrict__ PC, const bf16_t* __restrict__ PLR, bf16_t* __restrict__ UPD, float* __restrict__ DEC) {
;     ...
;         bf16_t* up = UPD + ((size_t)(combo * 256 + n)) * 32768;
; #pragma unroll
;         for (int nt = 0; nt < 4; ++nt)
; #pragma unroll
;             for (int e = 0; e < 16; ++e) { const int dv = 32 * wid + (e & 3) + 8 * (e >> 2) + 4 * h, dk = 32 * nt + r; up[dv * 128 + dk] = f2bf(acc[nt][e]); }
;         if (tid < 128) DEC[(size_t)(combo * 256 + n) * 128 + tid] = __expf(Gb[jb * 129 + tid]);
;         __syncthreads();
	v_mfma_f32_32x32x16_bf16 v[0:15], v[126:129], v[130:133], v[0:15]
	v_lshl_add_u64 v[126:127], v[72:73], 1, s[0:1]
	s_nop 1
	global_store_short v[126:127], v48, off
	v_cvt_pk_bf16_f32 v125, v49, v65
	v_lshl_add_u64 v[48:49], v[90:91], 1, s[0:1]
	global_store_short v[48:49], v125, off offset:256
	v_cvt_pk_bf16_f32 v50, v50, v65
	global_store_short v[48:49], v50, off offset:512
	v_cvt_pk_bf16_f32 v50, v51, v65
	global_store_short v[48:49], v50, off offset:768
	v_cvt_pk_bf16_f32 v50, v52, v65
	global_store_short v[48:49], v50, off offset:2048
	v_cvt_pk_bf16_f32 v50, v53, v65
	global_store_short v[48:49], v50, off offset:2304
	v_cvt_pk_bf16_f32 v50, v54, v65
	global_store_short v[48:49], v50, off offset:2560
	v_cvt_pk_bf16_f32 v50, v55, v65
	global_store_short v[48:49], v50, off offset:2816
	v_lshl_add_u64 v[50:51], v[74:75], 1, s[0:1]
	v_cvt_pk_bf16_f32 v52, v56, v65
	global_store_short v[50:51], v52, off
	v_lshl_add_u64 v[50:51], v[76:77], 1, s[0:1]
	v_cvt_pk_bf16_f32 v52, v57, v65
	global_store_short v[50:51], v52, off
	v_lshl_add_u64 v[50:51], v[78:79], 1, s[0:1]
	v_cvt_pk_bf16_f32 v52, v58, v65
	global_store_short v[50:51], v52, off
	v_lshl_add_u64 v[50:51], v[80:81], 1, s[0:1]
	v_cvt_pk_bf16_f32 v52, v59, v65
	global_store_short v[50:51], v52, off
	v_lshl_add_u64 v[50:51], v[82:83], 1, s[0:1]
	v_cvt_pk_bf16_f32 v52, v60, v65
	global_store_short v[50:51], v52, off
	v_lshl_add_u64 v[50:51], v[84:85], 1, s[0:1]
	v_cvt_pk_bf16_f32 v52, v61, v65
	global_store_short v[50:51], v52, off
	v_lshl_add_u64 v[50:51], v[86:87], 1, s[0:1]
	v_cvt_pk_bf16_f32 v52, v62, v65
	global_store_short v[50:51], v52, off
	v_lshl_add_u64 v[50:51], v[88:89], 1, s[0:1]
	v_cvt_pk_bf16_f32 v52, v63, v65
	global_store_short v[50:51], v52, off
	v_cvt_pk_bf16_f32 v32, v32, v65
	global_store_short v[48:49], v32, off offset:64
	v_cvt_pk_bf16_f32 v50, v33, v65
	v_lshl_add_u64 v[32:33], v[92:93], 1, s[0:1]
	global_store_short v[32:33], v50, off offset:64
	v_cvt_pk_bf16_f32 v34, v34, v65
	v_lshl_add_u64 v[50:51], v[94:95], 1, s[0:1]
	global_store_short v[50:51], v34, off offset:64
	v_cvt_pk_bf16_f32 v52, v35, v65
	v_lshl_add_u64 v[34:35], v[96:97], 1, s[0:1]
	global_store_short v[34:35], v52, off offset:64
	v_cvt_pk_bf16_f32 v36, v36, v65
	v_lshl_add_u64 v[52:53], v[98:99], 1, s[0:1]
	global_store_short v[52:53], v36, off offset:64
	v_cvt_pk_bf16_f32 v54, v37, v65
	v_lshl_add_u64 v[36:37], v[100:101], 1, s[0:1]
	global_store_short v[36:37], v54, off offset:64
	v_cvt_pk_bf16_f32 v38, v38, v65
	v_lshl_add_u64 v[54:55], v[102:103], 1, s[0:1]
	global_store_short v[54:55], v38, off offset:64
	v_cvt_pk_bf16_f32 v56, v39, v65
	v_lshl_add_u64 v[38:39], v[104:105], 1, s[0:1]
	global_store_short v[38:39], v56, off offset:64
	v_cvt_pk_bf16_f32 v40, v40, v65
	v_lshl_add_u64 v[56:57], v[106:107], 1, s[0:1]
	global_store_short v[56:57], v40, off offset:64
	v_cvt_pk_bf16_f32 v58, v41, v65
	v_lshl_add_u64 v[40:41], v[108:109], 1, s[0:1]
	global_store_short v[40:41], v58, off offset:64
	v_cvt_pk_bf16_f32 v42, v42, v65
	v_lshl_add_u64 v[58:59], v[110:111], 1, s[0:1]
	global_store_short v[58:59], v42, off offset:64
	v_cvt_pk_bf16_f32 v60, v43, v65
	v_lshl_add_u64 v[42:43], v[112:113], 1, s[0:1]
	global_store_short v[42:43], v60, off offset:64
	v_cvt_pk_bf16_f32 v44, v44, v65
	v_lshl_add_u64 v[60:61], v[114:115], 1, s[0:1]
	global_store_short v[60:61], v44, off offset:64
	v_cvt_pk_bf16_f32 v62, v45, v65
	v_lshl_add_u64 v[44:45], v[116:117], 1, s[0:1]
	global_store_short v[44:45], v62, off offset:64
	v_cvt_pk_bf16_f32 v46, v46, v65
	v_lshl_add_u64 v[62:63], v[118:119], 1, s[0:1]
	global_store_short v[62:63], v46, off offset:64
	v_cvt_pk_bf16_f32 v125, v47, v65
	v_lshl_add_u64 v[46:47], v[120:121], 1, s[0:1]
	global_store_short v[46:47], v125, off offset:64
	v_cvt_pk_bf16_f32 v16, v16, v65
	global_store_short v[48:49], v16, off offset:128
	v_cvt_pk_bf16_f32 v16, v17, v65
	global_store_short v[32:33], v16, off offset:128
	v_cvt_pk_bf16_f32 v16, v18, v65
	global_store_short v[50:51], v16, off offset:128
	v_cvt_pk_bf16_f32 v16, v19, v65
	global_store_short v[34:35], v16, off offset:128
	v_cvt_pk_bf16_f32 v16, v20, v65
	global_store_short v[52:53], v16, off offset:128
	v_cvt_pk_bf16_f32 v16, v21, v65
	global_store_short v[36:37], v16, off offset:128
	v_cvt_pk_bf16_f32 v16, v22, v65
	global_store_short v[54:55], v16, off offset:128
	v_cvt_pk_bf16_f32 v16, v23, v65
	global_store_short v[38:39], v16, off offset:128
	v_cvt_pk_bf16_f32 v16, v24, v65
	global_store_short v[56:57], v16, off offset:128
	v_cvt_pk_bf16_f32 v16, v25, v65
	global_store_short v[40:41], v16, off offset:128
	v_cvt_pk_bf16_f32 v16, v26, v65
	global_store_short v[58:59], v16, off offset:128
	v_cvt_pk_bf16_f32 v16, v27, v65
	global_store_short v[42:43], v16, off offset:128
	v_cvt_pk_bf16_f32 v16, v28, v65
	global_store_short v[60:61], v16, off offset:128
	v_cvt_pk_bf16_f32 v16, v29, v65
	global_store_short v[44:45], v16, off offset:128
	v_cvt_pk_bf16_f32 v16, v30, v65
	global_store_short v[62:63], v16, off offset:128
	v_cvt_pk_bf16_f32 v16, v31, v65
	global_store_short v[46:47], v16, off offset:128
	v_cvt_pk_bf16_f32 v0, v0, v65
	global_store_short v[48:49], v0, off offset:192
	v_cvt_pk_bf16_f32 v0, v1, v65
	global_store_short v[32:33], v0, off offset:192
	v_cvt_pk_bf16_f32 v0, v2, v65
	global_store_short v[50:51], v0, off offset:192
	v_cvt_pk_bf16_f32 v0, v3, v65
	global_store_short v[34:35], v0, off offset:192
	v_cvt_pk_bf16_f32 v0, v4, v65
	global_store_short v[52:53], v0, off offset:192
	v_cvt_pk_bf16_f32 v0, v5, v65
	global_store_short v[36:37], v0, off offset:192
	v_cvt_pk_bf16_f32 v0, v6, v65
	global_store_short v[54:55], v0, off offset:192
	v_cvt_pk_bf16_f32 v0, v7, v65
	global_store_short v[38:39], v0, off offset:192
	v_cvt_pk_bf16_f32 v0, v8, v65
	global_store_short v[56:57], v0, off offset:192
	v_cvt_pk_bf16_f32 v0, v9, v65
	global_store_short v[40:41], v0, off offset:192
	v_cvt_pk_bf16_f32 v0, v10, v65
	global_store_short v[58:59], v0, off offset:192
	v_cvt_pk_bf16_f32 v0, v11, v65
	global_store_short v[42:43], v0, off offset:192
	v_cvt_pk_bf16_f32 v0, v12, v65
	global_store_short v[60:61], v0, off offset:192
	v_cvt_pk_bf16_f32 v0, v13, v65
	global_store_short v[44:45], v0, off offset:192
	v_cvt_pk_bf16_f32 v0, v14, v65
	global_store_short v[62:63], v0, off offset:192
	v_cvt_pk_bf16_f32 v0, v15, v65
	global_store_short v[46:47], v0, off offset:192
	s_and_saveexec_b64 s[0:1], vcc
	s_cbranch_execz .LBB0_222
	v_add_u32_e32 v0, s2, v69
	ds_read_b32 v0, v0
	s_lshl_b64 s[2:3], s[28:29], 9
	s_waitcnt lgkmcnt(0)
	v_mul_f32_e32 v0, 0x3fb8aa3b, v0
	v_exp_f32_e32 v2, v0
	v_lshl_add_u64 v[0:1], v[66:67], 0, s[2:3]
	global_store_dword v[0:1], v2, off
	s_branch .LBB0_222

; __device__ __forceinline__ void gla_c3(const Args& a, int l, unsigned char* sm, const bf16_t* __restrict__ PC, const bf16_t* __restrict__ PLR, const bf16_t* __restrict__ UPD, bf16_t* __restrict__ OC) {
;     ...
; #pragma unroll
;             for (int mi = 0; mi < 2; ++mi) {
; #pragma unroll
;                 for (int ks = 0; ks < 4; ++ks) {
;                     const bf16x8 av = *(const bf16x8*)(Aa + (32 * mi + r) * 72 + ks * 16 + 8 * h);
;                     const bf16x8 bv = *(const bf16x8*)(vT + (32 * wid + r) * 72 + ks * 16 + 8 * h);
;                     accO[mi] = __builtin_amdgcn_mfma_f32_32x32x16_bf16(av, bv, accO[mi], 0, 0, 0);
;                 }
; #pragma unroll
;                 for (int ks = 0; ks < 8; ++ks) {
;                     const bf16x8 av = *(const bf16x8*)(qeL + (32 * mi + r) * 136 + ks * 16 + 8 * h);
;                     accO[mi] = __builtin_amdgcn_mfma_f32_32x32x16_bf16(av, sfr[ks], accO[mi], 0, 0, 0);
;                 }
;             }
.LBB0_455:
	s_or_b64 exec, exec, s[34:35]
	s_waitcnt lgkmcnt(0)
	s_barrier
	ds_read_b128 v[36:39], v87
	ds_read_b128 v[204:207], v105
	ds_read_b128 v[40:43], v87 offset:32
	ds_read_b128 v[208:211], v105 offset:32
	ds_read_b128 v[44:47], v87 offset:64
	ds_read_b128 v[212:215], v105 offset:64
	ds_read_b128 v[140:143], v87 offset:96
	ds_read_b128 v[216:219], v105 offset:96
	s_mov_b32 s47, 1
	s_mov_b64 s[28:29], 0
	s_and_b64 vcc, exec, s[4:5]
	s_waitcnt lgkmcnt(6)
	v_mfma_f32_32x32x16_bf16 v[0:15], v[204:207], v[36:39], v[0:15]
	ds_read_b128 v[204:207], v106 offset:47872
	s_waitcnt lgkmcnt(5)
	v_mfma_f32_32x32x16_bf16 v[0:15], v[208:211], v[40:43], v[0:15]
	ds_read_b128 v[208:211], v106 offset:47904
	s_waitcnt lgkmcnt(4)
	v_mfma_f32_32x32x16_bf16 v[0:15], v[212:215], v[44:47], v[0:15]
	ds_read_b128 v[212:215], v106 offset:47936
	s_waitcnt lgkmcnt(3)
	v_mfma_f32_32x32x16_bf16 v[0:15], v[216:219], v[140:143], v[0:15]
	ds_read_b128 v[216:219], v106 offset:47968
	s_waitcnt vmcnt(7) lgkmcnt(3)
	v_mfma_f32_32x32x16_bf16 v[0:15], v[204:207], v[78:81], v[0:15]
	ds_read_b128 v[204:207], v106 offset:48000
	s_waitcnt vmcnt(6) lgkmcnt(3)
	v_mfma_f32_32x32x16_bf16 v[0:15], v[208:211], v[74:77], v[0:15]
	ds_read_b128 v[208:211], v106 offset:48032
	s_waitcnt vmcnt(5) lgkmcnt(3)
	v_mfma_f32_32x32x16_bf16 v[0:15], v[212:215], v[70:73], v[0:15]
	ds_read_b128 v[212:215], v106 offset:48064
	s_waitcnt vmcnt(4) lgkmcnt(3)
	v_mfma_f32_32x32x16_bf16 v[0:15], v[216:219], v[66:69], v[0:15]
	ds_read_b128 v[216:219], v106 offset:48096
	s_waitcnt vmcnt(3) lgkmcnt(3)
	v_mfma_f32_32x32x16_bf16 v[0:15], v[204:207], v[60:63], v[0:15]
	ds_read_b128 v[204:207], v105 offset:4608
	s_waitcnt vmcnt(2) lgkmcnt(3)
	v_mfma_f32_32x32x16_bf16 v[0:15], v[208:211], v[56:59], v[0:15]
	ds_read_b128 v[208:211], v105 offset:4640
	s_waitcnt vmcnt(1) lgkmcnt(3)
	v_mfma_f32_32x32x16_bf16 v[0:15], v[212:215], v[52:55], v[0:15]
	ds_read_b128 v[212:215], v105 offset:4672
	s_waitcnt vmcnt(0) lgkmcnt(3)
	v_mfma_f32_32x32x16_bf16 v[0:15], v[216:219], v[48:51], v[0:15]
	ds_read_b128 v[216:219], v105 offset:4704
	s_waitcnt lgkmcnt(3)
	v_mfma_f32_32x32x16_bf16 v[16:31], v[204:207], v[36:39], v[16:31]
	ds_read_b128 v[204:207], v106 offset:56576
	s_waitcnt lgkmcnt(3)
	v_mfma_f32_32x32x16_bf16 v[16:31], v[208:211], v[40:43], v[16:31]
	ds_read_b128 v[208:211], v106 offset:56608
	s_waitcnt lgkmcnt(3)
	v_mfma_f32_32x32x16_bf16 v[16:31], v[212:215], v[44:47], v[16:31]
	ds_read_b128 v[212:215], v106 offset:56640
	s_waitcnt lgkmcnt(3)
	v_mfma_f32_32x32x16_bf16 v[16:31], v[216:219], v[140:143], v[16:31]
	ds_read_b128 v[216:219], v106 offset:56672
	s_waitcnt lgkmcnt(3)
	v_mfma_f32_32x32x16_bf16 v[16:31], v[204:207], v[78:81], v[16:31]
	ds_read_b128 v[204:207], v106 offset:56704
	s_waitcnt lgkmcnt(3)
	v_mfma_f32_32x32x16_bf16 v[16:31], v[208:211], v[74:77], v[16:31]
	ds_read_b128 v[208:211], v106 offset:56736
	s_waitcnt lgkmcnt(3)
	v_mfma_f32_32x32x16_bf16 v[16:31], v[212:215], v[70:73], v[16:31]
	ds_read_b128 v[212:215], v106 offset:56768
	s_waitcnt lgkmcnt(3)
	v_mfma_f32_32x32x16_bf16 v[16:31], v[216:219], v[66:69], v[16:31]
	ds_read_b128 v[216:219], v106 offset:56800
	s_waitcnt lgkmcnt(3)
	v_mfma_f32_32x32x16_bf16 v[16:31], v[204:207], v[60:63], v[16:31]
	s_waitcnt lgkmcnt(2)
	v_mfma_f32_32x32x16_bf16 v[16:31], v[208:211], v[56:59], v[16:31]
	s_waitcnt lgkmcnt(1)
	v_mfma_f32_32x32x16_bf16 v[16:31], v[212:215], v[52:55], v[16:31]
	s_waitcnt lgkmcnt(0)
	s_barrier
	v_mfma_f32_32x32x16_bf16 v[16:31], v[216:219], v[48:51], v[16:31]
	s_cbranch_vccnz .LBB0_453
